# SEAM3 (placement-verified mode): each recurrence workgroup waits only for the 2-3 XCCs that produced its batch's P3 tiles (their arrival counters, bumped after that XCC's L2 write-back) instead of the
# speedup vs baseline: 1.0032x; 1.0032x over previous
; __device__ __forceinline__ unsigned xb_ld(unsigned* p)              { return __hip_atomic_load(p, __ATOMIC_RELAXED, __HIP_MEMORY_SCOPE_AGENT); }
; __device__ __forceinline__ unsigned xb_add(unsigned* p, unsigned v) { return __hip_atomic_fetch_add(p, v, __ATOMIC_RELAXED, __HIP_MEMORY_SCOPE_AGENT); }
; #define XB_SPIN(cond, bar) do { unsigned _sp = 0; while (cond) { __builtin_amdgcn_s_sleep(1); \
;     if ((++_sp & 255u) == 0u) { if (xb_ld(&(bar)[XB_TMO])) break; if (_sp > XB_SPIN_CAP) { atomicAdd(&(bar)[XB_TMO], 1u); break; } } } } while (0)
; #define SEAM(k) do { if (IN(k) && IN((k) + 1)) xcd_barrier(bar); STAMP((k) + 1); } while (0)
; __device__ __forceinline__ void xcd_barrier(const XcdBarrier& b) {
;     asm volatile("s_waitcnt vmcnt(0)" ::: "memory");
;     __syncthreads();
;     if (threadIdx.x == 0) {
;         unsigned* bar = b.bar;
;         __builtin_amdgcn_s_waitcnt(0);
;         unsigned nloc = b.st[0], nx = b.st[1];
;         if (nloc == 0u) { xcd_barrier_complete(bar, b.x, nloc, nx); b.st[0] = nloc; b.st[1] = nx; }
;         const unsigned old = xb_add(&bar[XB_XSUB(b.x)], 1u);
;         const unsigned gen = old / nloc;
;         if (old + 1u == (gen + 1u) * nloc) {
;             __builtin_amdgcn_fence(__ATOMIC_RELEASE, "agent");
;             asm volatile("s_waitcnt vmcnt(0)" ::: "memory");
;             const unsigned og = xb_add(&bar[XB_TOP], 1u);
;             const unsigned tg = og / nx;
;             if (og + 1u == (tg + 1u) * nx) xb_add(&bar[XB_TOPGEN], 1u);
;             else XB_SPIN(xb_ld(&bar[XB_TOPGEN]) == tg, bar);
;             __builtin_amdgcn_fence(__ATOMIC_ACQUIRE, "agent");
;             xb_add(&bar[XB_XGEN(b.x)], 1u);
;             asm volatile("s_waitcnt vmcnt(0)" ::: "memory");
;         } else {
;             XB_SPIN(xb_ld(&bar[XB_XGEN(b.x)]) == gen, bar);
;             __builtin_amdgcn_fence(__ATOMIC_ACQUIRE, "agent");
;             asm volatile("s_waitcnt vmcnt(0)" ::: "memory");
;         }
;     }
;     __syncthreads();
; }
; __global__ void __launch_bounds__(512, 2) fwd_megakernel(Args a) {
;     ...
;     SEAM(3);
.Ls3_notleader:
	s_cmp_gt_u32 s2, 63
	s_cbranch_scc1 .Ls3_close
	v_mov_b32_e32 v14, 0x27e08
	s_mov_b32 s99, 0
.Ls3_fl:
	ds_read_b32 v15, v14
	s_waitcnt lgkmcnt(0)
	v_readfirstlane_b32 s8, v15
	s_nop 3
	s_cmp_lg_u32 s8, 0
	s_cbranch_scc1 .Ls3_flok
	s_add_u32 s99, s99, 1
	s_cmp_gt_u32 s99, 0x100000
	s_cbranch_scc1 .Ls3_flok
	s_sleep 1
	s_branch .Ls3_fl
.Ls3_flok:
	s_cmp_lg_u32 s8, 2
	s_cbranch_scc1 .Ls3_slowspin
	s_and_b32 s8, s2, 7
	s_lshl_b32 s8, s8, 2
	s_mov_b32 s9, 0x65442100
	s_lshr_b32 s9, s9, s8
	s_and_b32 s9, s9, 15
	s_mov_b32 s99, 0x77653321
	s_lshr_b32 s99, s99, s8
	s_and_b32 s99, s99, 15
	s_add_u32 s8, s9, 1
	s_lshl_b32 s9, s9, 2
	s_lshl_b32 s8, s8, 2
	s_lshl_b32 s99, s99, 2
	v_mov_b32_e32 v0, s9
	v_mov_b32_e32 v1, s8
	v_mov_b32_e32 v2, s99
	v_add_u32_e32 v0, 0x3a00, v0
	v_add_u32_e32 v1, 0x3a00, v1
	v_add_u32_e32 v2, 0x3a00, v2
	global_load_dword v0, v0, s[10:11] sc1
	global_load_dword v1, v1, s[10:11] sc1
	global_load_dword v2, v2, s[10:11] sc1
	s_waitcnt vmcnt(0)
	v_lshlrev_b32_e32 v0, 8, v0
	v_lshlrev_b32_e32 v1, 8, v1
	v_lshlrev_b32_e32 v2, 8, v2
	v_add_u32_e32 v0, 0x2300, v0
	v_add_u32_e32 v1, 0x2300, v1
	v_add_u32_e32 v2, 0x2300, v2
	s_mov_b32 s99, 0
.Ls3_xs:
	global_load_dword v12, v0, s[10:11] sc1
	global_load_dword v13, v1, s[10:11] sc1
	global_load_dword v14, v2, s[10:11] sc1
	s_waitcnt vmcnt(0)
	v_cmp_ne_u32_e32 vcc, v12, v7
	v_cmp_ne_u32_e64 s[8:9], v13, v7
	s_and_b64 vcc, vcc, s[8:9]
	v_cmp_ne_u32_e64 s[8:9], v14, v7
	s_and_b64 vcc, vcc, s[8:9]
	s_cbranch_vccnz .Ls3_released
	s_add_u32 s99, s99, 1
	s_cmp_gt_u32 s99, 0x40000
	s_cbranch_scc1 .Ls3_released
	s_sleep 1
	s_branch .Ls3_xs
.Ls3_slowspin:
	v_mov_b32_e32 v5, 0x3000
	s_mov_b32 s99, 0

; __device__ __forceinline__ unsigned xb_ld(unsigned* p)              { return __hip_atomic_load(p, __ATOMIC_RELAXED, __HIP_MEMORY_SCOPE_AGENT); }
; __device__ __forceinline__ unsigned xb_add(unsigned* p, unsigned v) { return __hip_atomic_fetch_add(p, v, __ATOMIC_RELAXED, __HIP_MEMORY_SCOPE_AGENT); }
; #define XB_SPIN(cond, bar) do { unsigned _sp = 0; while (cond) { __builtin_amdgcn_s_sleep(1); \
;     if ((++_sp & 255u) == 0u) { if (xb_ld(&(bar)[XB_TMO])) break; if (_sp > XB_SPIN_CAP) { atomicAdd(&(bar)[XB_TMO], 1u); break; } } } } while (0)
; __device__ __forceinline__ void xcd_barrier(const XcdBarrier& b) {
;     asm volatile("s_waitcnt vmcnt(0)" ::: "memory");
;     __syncthreads();
;     if (threadIdx.x == 0) {
;         unsigned* bar = b.bar;
;         __builtin_amdgcn_s_waitcnt(0);
;         unsigned nloc = b.st[0], nx = b.st[1];
;         if (nloc == 0u) { xcd_barrier_complete(bar, b.x, nloc, nx); b.st[0] = nloc; b.st[1] = nx; }
;         const unsigned old = xb_add(&bar[XB_XSUB(b.x)], 1u);
;         const unsigned gen = old / nloc;
;         if (old + 1u == (gen + 1u) * nloc) {
;             __builtin_amdgcn_fence(__ATOMIC_RELEASE, "agent");
;             asm volatile("s_waitcnt vmcnt(0)" ::: "memory");
;             const unsigned og = xb_add(&bar[XB_TOP], 1u);
;             const unsigned tg = og / nx;
;             if (og + 1u == (tg + 1u) * nx) xb_add(&bar[XB_TOPGEN], 1u);
;             else XB_SPIN(xb_ld(&bar[XB_TOPGEN]) == tg, bar);
;             __builtin_amdgcn_fence(__ATOMIC_ACQUIRE, "agent");
;             xb_add(&bar[XB_XGEN(b.x)], 1u);
;             asm volatile("s_waitcnt vmcnt(0)" ::: "memory");
;         } else {
;             XB_SPIN(xb_ld(&bar[XB_XGEN(b.x)]) == gen, bar);
;             __builtin_amdgcn_fence(__ATOMIC_ACQUIRE, "agent");
;             asm volatile("s_waitcnt vmcnt(0)" ::: "memory");
;         }
;     }
;     __syncthreads();
; }
.Ls3_other:
	s_mov_b64 exec, s[4:5]
	v_readfirstlane_b32 s6, v188
	s_nop 3
	s_cmp_lg_u32 s6, 64
	s_cbranch_scc1 .Ls3_close
	v_and_b32_e32 v0, 63, v188
	v_lshlrev_b32_e32 v1, 2, v0
	v_add_u32_e32 v1, 0x3a00, v1
	v_readlane_b32 s10, v248, 0
	v_readlane_b32 s11, v248, 1
	v_and_b32_e32 v6, 7, v0
	v_lshlrev_b32_e32 v6, 2, v6
	s_nop 4
	global_load_dword v2, v1, s[10:11] sc1
	global_load_dword v3, v1, s[10:11] offset:256 sc1
	global_load_dword v4, v1, s[10:11] offset:512 sc1
	global_load_dword v5, v1, s[10:11] offset:768 sc1
	s_waitcnt vmcnt(0)
	ds_bpermute_b32 v7, v6, v2
	s_waitcnt lgkmcnt(0)
	v_xor_b32_e32 v2, v2, v7
	v_xor_b32_e32 v3, v3, v7
	v_xor_b32_e32 v4, v4, v7
	v_xor_b32_e32 v5, v5, v7
	v_or3_b32 v2, v2, v3, v4
	v_or_b32_e32 v2, v2, v5
	v_mov_b32_e32 v8, 1
	v_lshlrev_b32_e32 v8, v7, v8
	v_cmp_ne_u32_e32 vcc, 0, v2
	v_cmp_eq_u32_e64 s[6:7], 0, v7
	s_or_b64 s[6:7], vcc, s[6:7]
	v_readlane_b32 s8, v8, 0
	v_readlane_b32 s9, v8, 1
	s_nop 1
	s_or_b32 s8, s8, s9
	v_readlane_b32 s9, v8, 2
	s_nop 1
	s_or_b32 s8, s8, s9
	v_readlane_b32 s9, v8, 3
	s_nop 1
	s_or_b32 s8, s8, s9
	v_readlane_b32 s9, v8, 4
	s_nop 1
	s_or_b32 s8, s8, s9
	v_readlane_b32 s9, v8, 5
	s_nop 1
	s_or_b32 s8, s8, s9
	v_readlane_b32 s9, v8, 6
	s_nop 1
	s_or_b32 s8, s8, s9
	v_readlane_b32 s9, v8, 7
	s_nop 1
	s_or_b32 s8, s8, s9
	s_bcnt1_i32_b32 s8, s8
	s_cmp_eq_u64 s[6:7], 0
	s_cselect_b32 s9, 1, 0
	s_cmp_eq_u32 s8, 8
	s_cselect_b32 s9, s9, 0
	s_add_u32 s9, s9, 1
	v_mov_b32_e32 v2, s9
	v_mov_b32_e32 v3, 0x27e08
	ds_write_b32 v3, v2

; __device__ __forceinline__ unsigned xb_ld(unsigned* p)              { return __hip_atomic_load(p, __ATOMIC_RELAXED, __HIP_MEMORY_SCOPE_AGENT); }
; __device__ __forceinline__ unsigned xb_add(unsigned* p, unsigned v) { return __hip_atomic_fetch_add(p, v, __ATOMIC_RELAXED, __HIP_MEMORY_SCOPE_AGENT); }
; #define XB_SPIN(cond, bar) do { unsigned _sp = 0; while (cond) { __builtin_amdgcn_s_sleep(1); \
;     if ((++_sp & 255u) == 0u) { if (xb_ld(&(bar)[XB_TMO])) break; if (_sp > XB_SPIN_CAP) { atomicAdd(&(bar)[XB_TMO], 1u); break; } } } } while (0)
; #define SEAM(k) do { if (IN(k) && IN((k) + 1)) xcd_barrier(bar); STAMP((k) + 1); } while (0)
; __device__ __forceinline__ void xcd_barrier(const XcdBarrier& b) {
;     asm volatile("s_waitcnt vmcnt(0)" ::: "memory");
;     __syncthreads();
;     if (threadIdx.x == 0) {
;         unsigned* bar = b.bar;
;         __builtin_amdgcn_s_waitcnt(0);
;         unsigned nloc = b.st[0], nx = b.st[1];
;         if (nloc == 0u) { xcd_barrier_complete(bar, b.x, nloc, nx); b.st[0] = nloc; b.st[1] = nx; }
;         const unsigned old = xb_add(&bar[XB_XSUB(b.x)], 1u);
;         const unsigned gen = old / nloc;
;         if (old + 1u == (gen + 1u) * nloc) {
;             __builtin_amdgcn_fence(__ATOMIC_RELEASE, "agent");
;             asm volatile("s_waitcnt vmcnt(0)" ::: "memory");
;             const unsigned og = xb_add(&bar[XB_TOP], 1u);
;             const unsigned tg = og / nx;
;             if (og + 1u == (tg + 1u) * nx) xb_add(&bar[XB_TOPGEN], 1u);
;             else XB_SPIN(xb_ld(&bar[XB_TOPGEN]) == tg, bar);
;             __builtin_amdgcn_fence(__ATOMIC_ACQUIRE, "agent");
;             xb_add(&bar[XB_XGEN(b.x)], 1u);
;             asm volatile("s_waitcnt vmcnt(0)" ::: "memory");
;         } else {
;             XB_SPIN(xb_ld(&bar[XB_XGEN(b.x)]) == gen, bar);
;             __builtin_amdgcn_fence(__ATOMIC_ACQUIRE, "agent");
;             asm volatile("s_waitcnt vmcnt(0)" ::: "memory");
;         }
;     }
;     __syncthreads();
; }
; __global__ void __launch_bounds__(512, 2) fwd_megakernel(Args a) {
;     ...
;     SEAM(4);
.LBB0_532:
	s_cmp_gt_i32 s83, 5
	s_cselect_b64 s[0:1], -1, 0
	s_and_b64 s[4:5], s[84:85], s[0:1]
	s_andn2_b64 vcc, exec, s[4:5]
	s_cbranch_vccnz .LBB0_586
	s_waitcnt vmcnt(0)
	s_waitcnt vmcnt(0) lgkmcnt(0)
	s_barrier
	s_mov_b64 s[4:5], exec
	v_readlane_b32 s6, v248, 2
	v_readlane_b32 s7, v248, 3
	s_and_b64 s[6:7], s[4:5], s[6:7]
	s_mov_b64 exec, s[6:7]
	s_cbranch_execz .LBB0_585
	v_mov_b32_e32 v0, 0x27e08
	ds_read_b32 v2, v0
	v_readlane_b32 s10, v248, 0
	v_readlane_b32 s11, v248, 1
	s_lshl_b32 s6, s3, 8
	v_mov_b32_e32 v4, 1
	s_add_u32 s6, s10, s6
	s_addc_u32 s7, s11, 0
	v_mov_b32_e32 v13, 0x3900
	s_waitcnt lgkmcnt(0)
	v_readfirstlane_b32 s8, v2
	s_nop 3
	s_cmp_lg_u32 s8, 2
	s_cbranch_scc1 .Ls4_slowpre
	v_mov_b32_e32 v5, 0x1000
	global_atomic_add v6, v5, v4, s[6:7] offset:1024 sc0
	v_mov_b32_e32 v5, 0x2000
	s_mov_b32 s99, 0
	s_waitcnt vmcnt(0)
	v_lshrrev_b32_e32 v7, 5, v6
	v_and_b32_e32 v8, 31, v6
	v_cmp_eq_u32_e32 vcc, 31, v8
	s_cbranch_vccz .Ls4_spin
	global_atomic_add v5, v4, s[6:7] offset:1024
	s_branch .Ls4_rel

; __device__ __forceinline__ unsigned xb_ld(unsigned* p)              { return __hip_atomic_load(p, __ATOMIC_RELAXED, __HIP_MEMORY_SCOPE_AGENT); }
; __device__ __forceinline__ unsigned xb_add(unsigned* p, unsigned v) { return __hip_atomic_fetch_add(p, v, __ATOMIC_RELAXED, __HIP_MEMORY_SCOPE_AGENT); }
; #define XB_SPIN(cond, bar) do { unsigned _sp = 0; while (cond) { __builtin_amdgcn_s_sleep(1); \
;     if ((++_sp & 255u) == 0u) { if (xb_ld(&(bar)[XB_TMO])) break; if (_sp > XB_SPIN_CAP) { atomicAdd(&(bar)[XB_TMO], 1u); break; } } } } while (0)
; #define SEAM(k) do { if (IN(k) && IN((k) + 1)) xcd_barrier(bar); STAMP((k) + 1); } while (0)
; __device__ __forceinline__ void xcd_barrier(const XcdBarrier& b) {
;     asm volatile("s_waitcnt vmcnt(0)" ::: "memory");
;     __syncthreads();
;     if (threadIdx.x == 0) {
;         unsigned* bar = b.bar;
;         __builtin_amdgcn_s_waitcnt(0);
;         unsigned nloc = b.st[0], nx = b.st[1];
;         if (nloc == 0u) { xcd_barrier_complete(bar, b.x, nloc, nx); b.st[0] = nloc; b.st[1] = nx; }
;         const unsigned old = xb_add(&bar[XB_XSUB(b.x)], 1u);
;         const unsigned gen = old / nloc;
;         if (old + 1u == (gen + 1u) * nloc) {
;             __builtin_amdgcn_fence(__ATOMIC_RELEASE, "agent");
;             asm volatile("s_waitcnt vmcnt(0)" ::: "memory");
;             const unsigned og = xb_add(&bar[XB_TOP], 1u);
;             const unsigned tg = og / nx;
;             if (og + 1u == (tg + 1u) * nx) xb_add(&bar[XB_TOPGEN], 1u);
;             else XB_SPIN(xb_ld(&bar[XB_TOPGEN]) == tg, bar);
;             __builtin_amdgcn_fence(__ATOMIC_ACQUIRE, "agent");
;             xb_add(&bar[XB_XGEN(b.x)], 1u);
;             asm volatile("s_waitcnt vmcnt(0)" ::: "memory");
;         } else {
;             XB_SPIN(xb_ld(&bar[XB_XGEN(b.x)]) == gen, bar);
;             __builtin_amdgcn_fence(__ATOMIC_ACQUIRE, "agent");
;             asm volatile("s_waitcnt vmcnt(0)" ::: "memory");
;         }
;     }
;     __syncthreads();
; }
; __global__ void __launch_bounds__(512, 2) fwd_megakernel(Args a) {
;     ...
;     SEAM(5);
.LBB0_611:
	s_cmp_gt_i32 s83, 6
	s_cselect_b64 s[0:1], -1, 0
	s_and_b64 s[4:5], s[4:5], s[0:1]
	s_andn2_b64 vcc, exec, s[4:5]
	s_cbranch_vccnz .LBB0_665
	s_waitcnt vmcnt(0)
	s_waitcnt vmcnt(0) lgkmcnt(0)
	s_barrier
	s_mov_b64 s[4:5], exec
	v_readlane_b32 s6, v248, 2
	v_readlane_b32 s7, v248, 3
	s_and_b64 s[6:7], s[4:5], s[6:7]
	s_mov_b64 exec, s[6:7]
	s_cbranch_execz .LBB0_664
	v_mov_b32_e32 v0, 0x27e08
	ds_read_b32 v2, v0
	v_readlane_b32 s10, v248, 0
	v_readlane_b32 s11, v248, 1
	s_lshl_b32 s6, s3, 8
	v_mov_b32_e32 v4, 1
	s_add_u32 s6, s10, s6
	s_addc_u32 s7, s11, 0
	v_mov_b32_e32 v13, 0x3900
	s_waitcnt lgkmcnt(0)
	v_readfirstlane_b32 s8, v2
	s_nop 3
	s_cmp_lg_u32 s8, 2
	s_cbranch_scc1 .Ls5_slowpre
	v_mov_b32_e32 v5, 0x1000
	global_atomic_add v6, v5, v4, s[6:7] offset:1024 sc0
	v_mov_b32_e32 v5, 0x2000
	s_mov_b32 s99, 0
	s_waitcnt vmcnt(0)
	v_lshrrev_b32_e32 v7, 5, v6
	v_and_b32_e32 v8, 31, v6
	v_cmp_eq_u32_e32 vcc, 0, v8
	s_cbranch_vccz .Ls5_nb
	buffer_wbl2 sc1
	s_waitcnt vmcnt(0)
